# attention: waves 4-7 stage the next K/V tile at the top of the iteration (SIMD partners offset)
# speedup vs baseline: 1.0035x; 1.0024x over previous
.LBB0_231:
	s_bitcmp1_b32 s40, 0
	s_cselect_b32 s43, 0x8800, 0
	s_cmp_lt_u32 s97, 4
	s_cbranch_scc1 .Latt_top_done
	s_add_i32 s0, s40, -1
	s_cmp_ge_u32 s0, s38
	s_cbranch_scc1 .Latt_top_done
	s_sub_i32 s0, 0, s43
	v_add_u32_e32 v238, s0, v175
	s_waitcnt vmcnt(1)
	ds_write_b128 v238, v[124:127] offset:34816
	ds_write_b128 v238, v[116:119] offset:43520
	v_add_u32_e32 v238, s0, v176
	s_cmp_ge_u32 s40, s38
	s_waitcnt vmcnt(0)
	ds_write_b128 v238, v[140:143] offset:52224
	ds_write_b128 v238, v[132:135] offset:60928
	s_cbranch_scc1 .Latt_top_done
	v_lshl_add_u64 v[116:117], s[22:23], 0, v[144:145]
	v_add_co_u32_e32 v116, vcc, 0x14400000, v116
	v_lshl_add_u64 v[132:133], s[22:23], 0, v[162:163]
	s_nop 0
	v_addc_co_u32_e32 v117, vcc, 0, v117, vcc
	v_add_co_u32_e32 v134, vcc, 0x14400000, v132
	global_load_dwordx4 v[124:127], v[116:117], off
	s_nop 0
	global_load_dwordx4 v[116:119], v[116:117], off offset:256
	v_addc_co_u32_e32 v135, vcc, 0, v133, vcc
	v_add_co_u32_e32 v132, vcc, 0x144c0000, v132
	s_nop 1
	v_addc_co_u32_e32 v133, vcc, 0, v133, vcc
	global_load_dwordx4 v[140:143], v[134:135], off
	s_nop 0
	global_load_dwordx4 v[132:135], v[132:133], off
.Latt_top_done:
	s_sub_i32 s0, s39, 31
	s_cmp_gt_u32 s0, s41
	s_cbranch_scc1 .LBB0_235
	v_add_u32_e32 v168, s43, v178
	ds_read_b128 v[196:199], v168
	ds_read_b128 v[200:203], v195
	ds_read_b128 v[204:207], v195 offset:64
	ds_read_b128 v[208:211], v168 offset:64
	ds_read_b128 v[212:215], v168 offset:4352
	ds_read_b128 v[216:219], v168 offset:4416
	v_cvt_f32_i32_e32 v224, v194
	s_waitcnt lgkmcnt(4)
	v_mfma_f32_16x16x32_bf16 v[196:199], v[196:199], v[200:203], 0
	s_cmp_gt_u32 s39, s37
	v_cmp_gt_i32_e32 vcc, 0, v194
	s_cselect_b64 s[44:45], -1, 0
	s_waitcnt lgkmcnt(1)
	v_mfma_f32_16x16x32_bf16 v[200:203], v[212:215], v[200:203], 0
	ds_read_b128 v[212:215], v168 offset:128
	s_and_b64 vcc, s[44:45], vcc
	v_cmp_gt_i32_e64 s[4:5], 1, v194
	v_mfma_f32_16x16x32_bf16 v[196:199], v[208:211], v[204:207], v[196:199]
	ds_read_b128 v[208:211], v195 offset:128
	ds_read_b128 v[220:223], v168 offset:192
	s_and_b64 s[4:5], s[44:45], s[4:5]
	v_cmp_gt_i32_e64 s[6:7], 2, v194
	s_waitcnt lgkmcnt(3)
	v_mfma_f32_16x16x32_bf16 v[200:203], v[216:219], v[204:207], v[200:203]
	ds_read_b128 v[204:207], v195 offset:192
	ds_read_b128 v[216:219], v168 offset:4480
	v_cmp_gt_i32_e64 s[8:9], 3, v194
	v_cmp_gt_i32_e64 s[0:1], 16, v194
	s_waitcnt lgkmcnt(3)
	v_mfma_f32_16x16x32_bf16 v[196:199], v[212:215], v[208:211], v[196:199]
	ds_read_b128 v[212:215], v168 offset:4544
	s_and_b64 s[6:7], s[44:45], s[6:7]
	s_and_b64 s[8:9], s[44:45], s[8:9]
	s_waitcnt lgkmcnt(1)
	v_mfma_f32_16x16x32_bf16 v[200:203], v[216:219], v[208:211], v[200:203]
	v_cmp_gt_i32_e64 s[10:11], 17, v194
	s_and_b64 s[0:1], s[44:45], s[0:1]
	s_and_b64 s[10:11], s[44:45], s[10:11]
	v_mfma_f32_16x16x32_bf16 v[220:223], v[220:223], v[204:207], v[196:199]
	v_cmp_gt_i32_e64 s[12:13], 18, v194
	v_cmp_gt_i32_e64 s[14:15], 19, v194
	s_and_b64 s[12:13], s[44:45], s[12:13]
	s_waitcnt lgkmcnt(0)
	v_mfma_f32_16x16x32_bf16 v[202:205], v[212:215], v[204:207], v[200:203]
	ds_read_b128 v[206:209], v168 offset:8704
	ds_read_b128 v[210:213], v195 offset:34816
	ds_read_b128 v[214:217], v168 offset:13056
	v_mul_f32_e64 v197, -v149, v224
	v_fmamk_f32 v196, v220, 0x3e0293ee, v197
	v_add_f32_e32 v196, v153, v196
	v_cndmask_b32_e32 v198, v196, v192, vcc
	v_fmamk_f32 v196, v221, 0x3e0293ee, v197
	v_fmamk_f32 v200, v222, 0x3e0293ee, v197
	v_fmamk_f32 v201, v223, 0x3e0293ee, v197
	ds_read_b128 v[218:221], v195 offset:34880
	ds_read_b128 v[222:225], v168 offset:8768
	s_waitcnt lgkmcnt(3)
	v_mfma_f32_16x16x32_bf16 v[206:209], v[206:209], v[210:213], 0
	ds_read_b128 v[226:229], v168 offset:13120
	v_add_f32_e32 v196, v149, v196
	v_cndmask_b32_e64 v199, v196, v192, s[4:5]
	s_waitcnt lgkmcnt(3)
	v_mfma_f32_16x16x32_bf16 v[210:213], v[214:217], v[210:213], 0
	ds_read_b128 v[214:217], v168 offset:8832
	v_add_f32_e32 v200, v155, v200
	v_add_f32_e32 v201, v157, v201
	s_waitcnt lgkmcnt(2)
	v_mfma_f32_16x16x32_bf16 v[206:209], v[222:225], v[218:221], v[206:209]
	ds_read_b128 v[222:225], v195 offset:34944
	ds_read_b128 v[230:233], v168 offset:13184
	v_fmamk_f32 v202, v202, 0x3e0293ee, v197
	v_fmamk_f32 v203, v203, 0x3e0293ee, v197
	v_max3_f32 v196, v198, s33, v199
	v_cndmask_b32_e64 v200, v200, v192, s[6:7]
	v_cndmask_b32_e64 v201, v201, v192, s[8:9]
	v_add_f32_e32 v202, v151, v202
	v_add_f32_e32 v203, v159, v203
	v_fmamk_f32 v204, v204, 0x3e0293ee, v197
	v_fmamk_f32 v205, v205, 0x3e0293ee, v197
	v_max3_f32 v196, v196, v200, v201
	v_cndmask_b32_e64 v202, v202, v192, s[0:1]
	v_cndmask_b32_e64 v203, v203, v192, s[10:11]
	v_add_f32_e32 v204, v161, v204
	v_add_f32_e32 v205, v193, v205
	s_and_b64 s[14:15], s[44:45], s[14:15]
	s_waitcnt lgkmcnt(3)
	v_mfma_f32_16x16x32_bf16 v[210:213], v[226:229], v[218:221], v[210:213]
	ds_read_b128 v[218:221], v195 offset:35008
	ds_read_b128 v[226:229], v168 offset:8896
	v_max3_f32 v196, v196, v202, v203
	v_cndmask_b32_e64 v204, v204, v192, s[12:13]
	s_waitcnt lgkmcnt(3)
	v_mfma_f32_16x16x32_bf16 v[206:209], v[214:217], v[222:225], v[206:209]
	ds_read_b128 v[214:217], v168 offset:13248
	v_cndmask_b32_e64 v205, v205, v192, s[14:15]
	v_max3_f32 v196, v196, v204, v205
	v_mov_b32_e32 v234, v196
	s_nop 1
	v_permlane16_swap_b32_e32 v196, v234
	v_max_f32_e32 v234, v234, v234
	v_max_f32_e32 v196, v196, v196
	s_waitcnt lgkmcnt(3)
	v_mfma_f32_16x16x32_bf16 v[210:213], v[230:233], v[222:225], v[210:213]
	v_max_f32_e32 v196, v196, v234
	v_mov_b32_e32 v168, v196
	s_nop 1
	v_permlane32_swap_b32_e32 v196, v168
	s_waitcnt lgkmcnt(1)
	v_mfma_f32_16x16x32_bf16 v[206:209], v[226:229], v[218:221], v[206:209]
	v_max3_f32 v196, v167, v196, v168
	v_sub_f32_e32 v167, v167, v196
	v_exp_f32_e32 v167, v167
	s_waitcnt lgkmcnt(0)
	v_mfma_f32_16x16x32_bf16 v[210:213], v[214:217], v[218:221], v[210:213]
	s_nop 2
	v_fmamk_f32 v168, v206, 0x3e0293ee, v197
	v_add_f32_e32 v168, v153, v168
	v_cndmask_b32_e32 v206, v168, v192, vcc
	v_fmamk_f32 v168, v207, 0x3e0293ee, v197
	v_add_f32_e32 v168, v149, v168
	v_fmamk_f32 v208, v208, 0x3e0293ee, v197
	v_fmamk_f32 v209, v209, 0x3e0293ee, v197
	v_cndmask_b32_e64 v207, v168, v192, s[4:5]
	v_add_f32_e32 v208, v155, v208
	v_add_f32_e32 v209, v157, v209
	v_fmamk_f32 v210, v210, 0x3e0293ee, v197
	v_fmamk_f32 v211, v211, 0x3e0293ee, v197
	v_max3_f32 v168, v206, s33, v207
	v_cndmask_b32_e64 v208, v208, v192, s[6:7]
	v_cndmask_b32_e64 v209, v209, v192, s[8:9]
	v_add_f32_e32 v210, v151, v210
	v_add_f32_e32 v211, v159, v211
	v_fmamk_f32 v212, v212, 0x3e0293ee, v197
	v_fmac_f32_e32 v197, 0x3e0293ee, v213
	v_max3_f32 v168, v168, v208, v209
	v_cndmask_b32_e64 v210, v210, v192, s[0:1]
	v_cndmask_b32_e64 v211, v211, v192, s[10:11]
	v_add_f32_e32 v212, v161, v212
	v_add_f32_e32 v197, v193, v197
	v_max3_f32 v168, v168, v210, v211
	v_cndmask_b32_e64 v212, v212, v192, s[12:13]
	v_cndmask_b32_e64 v213, v197, v192, s[14:15]
	v_max3_f32 v168, v168, v212, v213
	v_mov_b32_e32 v197, v168
	s_nop 1
	v_permlane16_swap_b32_e32 v168, v197
	v_max_f32_e32 v197, v197, v197
	v_max_f32_e32 v168, v168, v168
	v_max_f32_e32 v168, v168, v197
	v_mov_b32_e32 v197, v168
	s_nop 1
	v_permlane32_swap_b32_e32 v168, v197
	v_max3_f32 v197, v166, v168, v197
	v_sub_f32_e32 v166, v166, v197
	v_exp_f32_e32 v166, v166
	v_cmp_neq_f32_e32 vcc, 1.0, v167
	v_cmp_neq_f32_e64 s[0:1], 1.0, v166
	s_or_b64 vcc, vcc, s[0:1]
	s_cbranch_vccz .LBB0_234
	v_mov_b32_e32 v168, v167
	v_pk_mul_f32 v[138:139], v[138:139], v[168:169] op_sel_hi:[1,0]
	v_pk_mul_f32 v[136:137], v[136:137], v[168:169] op_sel_hi:[1,0]
	v_pk_mul_f32 v[130:131], v[130:131], v[166:167] op_sel_hi:[1,0]
	v_pk_mul_f32 v[128:129], v[128:129], v[166:167] op_sel_hi:[1,0]
	v_pk_mul_f32 v[122:123], v[122:123], v[168:169] op_sel_hi:[1,0]
	v_pk_mul_f32 v[120:121], v[120:121], v[168:169] op_sel_hi:[1,0]
	v_pk_mul_f32 v[114:115], v[114:115], v[166:167] op_sel_hi:[1,0]
	v_pk_mul_f32 v[112:113], v[112:113], v[166:167] op_sel_hi:[1,0]
	v_pk_mul_f32 v[110:111], v[110:111], v[168:169] op_sel_hi:[1,0]
	v_pk_mul_f32 v[108:109], v[108:109], v[168:169] op_sel_hi:[1,0]
	v_pk_mul_f32 v[106:107], v[106:107], v[166:167] op_sel_hi:[1,0]
	v_pk_mul_f32 v[104:105], v[104:105], v[166:167] op_sel_hi:[1,0]
	v_pk_mul_f32 v[102:103], v[102:103], v[168:169] op_sel_hi:[1,0]
	v_pk_mul_f32 v[100:101], v[100:101], v[168:169] op_sel_hi:[1,0]
	v_pk_mul_f32 v[98:99], v[98:99], v[166:167] op_sel_hi:[1,0]
	v_pk_mul_f32 v[96:97], v[96:97], v[166:167] op_sel_hi:[1,0]
	v_pk_mul_f32 v[94:95], v[94:95], v[168:169] op_sel_hi:[1,0]
	v_pk_mul_f32 v[92:93], v[92:93], v[168:169] op_sel_hi:[1,0]
	v_pk_mul_f32 v[90:91], v[90:91], v[166:167] op_sel_hi:[1,0]
	v_pk_mul_f32 v[88:89], v[88:89], v[166:167] op_sel_hi:[1,0]
	v_pk_mul_f32 v[86:87], v[86:87], v[168:169] op_sel_hi:[1,0]
	v_pk_mul_f32 v[84:85], v[84:85], v[168:169] op_sel_hi:[1,0]
	v_pk_mul_f32 v[82:83], v[82:83], v[166:167] op_sel_hi:[1,0]
	v_pk_mul_f32 v[80:81], v[80:81], v[166:167] op_sel_hi:[1,0]
	v_pk_mul_f32 v[78:79], v[78:79], v[168:169] op_sel_hi:[1,0]
	v_pk_mul_f32 v[76:77], v[76:77], v[168:169] op_sel_hi:[1,0]
	v_pk_mul_f32 v[74:75], v[74:75], v[166:167] op_sel_hi:[1,0]
	v_pk_mul_f32 v[72:73], v[72:73], v[166:167] op_sel_hi:[1,0]
	v_pk_mul_f32 v[70:71], v[70:71], v[168:169] op_sel_hi:[1,0]
	v_pk_mul_f32 v[68:69], v[68:69], v[168:169] op_sel_hi:[1,0]
	v_pk_mul_f32 v[66:67], v[66:67], v[166:167] op_sel_hi:[1,0]
	v_pk_mul_f32 v[64:65], v[64:65], v[166:167] op_sel_hi:[1,0]
	v_pk_mul_f32 v[62:63], v[62:63], v[168:169] op_sel_hi:[1,0]
	v_pk_mul_f32 v[60:61], v[60:61], v[168:169] op_sel_hi:[1,0]
	v_pk_mul_f32 v[58:59], v[58:59], v[166:167] op_sel_hi:[1,0]
	v_pk_mul_f32 v[56:57], v[56:57], v[166:167] op_sel_hi:[1,0]
	v_pk_mul_f32 v[50:51], v[50:51], v[168:169] op_sel_hi:[1,0]
	v_pk_mul_f32 v[48:49], v[48:49], v[168:169] op_sel_hi:[1,0]
	v_pk_mul_f32 v[42:43], v[42:43], v[166:167] op_sel_hi:[1,0]
	v_pk_mul_f32 v[40:41], v[40:41], v[166:167] op_sel_hi:[1,0]
	v_pk_mul_f32 v[46:47], v[46:47], v[168:169] op_sel_hi:[1,0]
	v_pk_mul_f32 v[44:45], v[44:45], v[168:169] op_sel_hi:[1,0]
	v_pk_mul_f32 v[54:55], v[54:55], v[166:167] op_sel_hi:[1,0]
	v_pk_mul_f32 v[52:53], v[52:53], v[166:167] op_sel_hi:[1,0]
	v_pk_mul_f32 v[30:31], v[30:31], v[168:169] op_sel_hi:[1,0]
	v_pk_mul_f32 v[28:29], v[28:29], v[168:169] op_sel_hi:[1,0]
	v_pk_mul_f32 v[38:39], v[38:39], v[166:167] op_sel_hi:[1,0]
	v_pk_mul_f32 v[36:37], v[36:37], v[166:167] op_sel_hi:[1,0]
	v_pk_mul_f32 v[18:19], v[18:19], v[168:169] op_sel_hi:[1,0]
	v_pk_mul_f32 v[16:17], v[16:17], v[168:169] op_sel_hi:[1,0]
	v_pk_mul_f32 v[34:35], v[34:35], v[166:167] op_sel_hi:[1,0]
	v_pk_mul_f32 v[32:33], v[32:33], v[166:167] op_sel_hi:[1,0]
	v_pk_mul_f32 v[10:11], v[10:11], v[168:169] op_sel_hi:[1,0]
	v_pk_mul_f32 v[8:9], v[8:9], v[168:169] op_sel_hi:[1,0]
	v_pk_mul_f32 v[26:27], v[26:27], v[166:167] op_sel_hi:[1,0]
	v_pk_mul_f32 v[24:25], v[24:25], v[166:167] op_sel_hi:[1,0]
	v_pk_mul_f32 v[6:7], v[6:7], v[168:169] op_sel_hi:[1,0]
	v_pk_mul_f32 v[4:5], v[4:5], v[168:169] op_sel_hi:[1,0]
	v_pk_mul_f32 v[22:23], v[22:23], v[166:167] op_sel_hi:[1,0]
	v_pk_mul_f32 v[20:21], v[20:21], v[166:167] op_sel_hi:[1,0]
	v_pk_mul_f32 v[2:3], v[2:3], v[168:169] op_sel_hi:[1,0]
	v_pk_mul_f32 v[0:1], v[0:1], v[168:169] op_sel_hi:[1,0]
	v_pk_mul_f32 v[14:15], v[14:15], v[166:167] op_sel_hi:[1,0]
	v_pk_mul_f32 v[12:13], v[12:13], v[166:167] op_sel_hi:[1,0]

.LBB0_236:
	s_cmp_ge_u32 s97, 4
	s_cbranch_scc1 .LBB0_238
	s_sub_i32 s0, 0, s43
	v_add_u32_e32 v166, s0, v175
	s_waitcnt vmcnt(1)
	ds_write_b128 v166, v[124:127] offset:34816
	ds_write_b128 v166, v[116:119] offset:43520
	v_add_u32_e32 v166, s0, v176
	s_cmp_ge_u32 s40, s38
	s_waitcnt vmcnt(0)
	ds_write_b128 v166, v[140:143] offset:52224
	ds_write_b128 v166, v[132:135] offset:60928
	s_cbranch_scc1 .LBB0_238
	v_lshl_add_u64 v[116:117], s[22:23], 0, v[144:145]
	v_add_co_u32_e32 v116, vcc, 0x14400000, v116
	v_lshl_add_u64 v[132:133], s[22:23], 0, v[162:163]
	s_nop 0
	v_addc_co_u32_e32 v117, vcc, 0, v117, vcc
	v_add_co_u32_e32 v134, vcc, 0x14400000, v132
	global_load_dwordx4 v[124:127], v[116:117], off
	s_nop 0
	global_load_dwordx4 v[116:119], v[116:117], off offset:256
	v_addc_co_u32_e32 v135, vcc, 0, v133, vcc
	v_add_co_u32_e32 v132, vcc, 0x144c0000, v132
	s_nop 1
	v_addc_co_u32_e32 v133, vcc, 0, v133, vcc
	global_load_dwordx4 v[140:143], v[134:135], off
	s_nop 0
	global_load_dwordx4 v[132:135], v[132:133], off

.LBB0_544:
	s_cmp_lt_i32 s80, 6
	s_cselect_b64 s[0:1], -1, 0
	s_and_b64 s[0:1], s[0:1], s[4:5]
	s_andn2_b64 vcc, exec, s[0:1]
	s_cbranch_vccnz .LBB0_548
	s_lshl_b32 s0, s2, 3
	s_add_i32 s0, s97, s0
	s_cmpk_gt_i32 s0, 0x1fff
	s_cbranch_scc1 .LBB0_548
	s_lshl_b32 s3, s82, 3
	v_readlane_b32 s12, v239, 3
	v_readlane_b32 s13, v239, 4
	s_add_u32 s14, s70, 0x10100000
	s_addc_u32 s15, s71, 0
	v_lshlrev_b32_e32 v0, 4, v182
	v_add_u32_e32 v1, 0x1000, v0
	v_add_u32_e32 v2, 0x2000, v0
	v_add_u32_e32 v3, 0x3000, v0
	v_lshlrev_b32_e32 v4, 3, v182
	v_add_u32_e32 v5, 0x1000, v4
	v_xor_b32_e32 v7, 1, v182
	v_lshlrev_b32_e32 v8, 2, v7
	v_xor_b32_e32 v7, 2, v182
	v_lshlrev_b32_e32 v9, 2, v7
	v_xor_b32_e32 v7, 4, v182
	v_lshlrev_b32_e32 v10, 2, v7
	v_xor_b32_e32 v7, 8, v182
	v_lshlrev_b32_e32 v11, 2, v7
	v_xor_b32_e32 v7, 16, v182
	v_lshlrev_b32_e32 v12, 2, v7
	v_xor_b32_e32 v7, 32, v182
	v_lshlrev_b32_e32 v13, 2, v7
	v_mov_b32_e32 v14, 0x358637bd
	global_load_dwordx4 v[16:19], v0, s[66:67] offset:0
	global_load_dwordx4 v[20:23], v0, s[66:67] offset:1024
	global_load_dwordx4 v[24:27], v0, s[66:67] offset:2048
	global_load_dwordx4 v[28:31], v0, s[66:67] offset:3072
	global_load_dwordx4 v[32:35], v1, s[66:67] offset:0
	global_load_dwordx4 v[36:39], v1, s[66:67] offset:1024
	global_load_dwordx4 v[40:43], v1, s[66:67] offset:2048
	global_load_dwordx4 v[44:47], v1, s[66:67] offset:3072
	global_load_dwordx4 v[48:51], v2, s[66:67] offset:0
	global_load_dwordx4 v[52:55], v2, s[66:67] offset:1024
	global_load_dwordx4 v[56:59], v2, s[66:67] offset:2048
	global_load_dwordx4 v[60:63], v2, s[66:67] offset:3072
	global_load_dwordx4 v[64:67], v3, s[66:67] offset:0
	global_load_dwordx4 v[68:71], v3, s[66:67] offset:1024
	global_load_dwordx4 v[72:75], v3, s[66:67] offset:2048
	global_load_dwordx4 v[76:79], v3, s[66:67] offset:3072
.Lp5_row:
	s_lshl_b32 s4, s0, 14
	s_add_u32 s6, s12, s4
	s_addc_u32 s7, s13, 0
	s_add_u32 s8, s68, s4
	s_addc_u32 s9, s69, 0
	s_lshl_b32 s4, s0, 13
	s_add_u32 s10, s14, s4
	s_addc_u32 s11, s15, 0
	global_load_dwordx2 v[144:145], v4, s[10:11] offset:0
	global_load_dwordx4 v[80:83], v0, s[6:7] offset:0
	global_load_dwordx2 v[146:147], v4, s[10:11] offset:512
	global_load_dwordx4 v[84:87], v0, s[6:7] offset:1024
	global_load_dwordx2 v[148:149], v4, s[10:11] offset:1024
	global_load_dwordx4 v[88:91], v0, s[6:7] offset:2048
	global_load_dwordx2 v[150:151], v4, s[10:11] offset:1536
	global_load_dwordx4 v[92:95], v0, s[6:7] offset:3072
	global_load_dwordx2 v[152:153], v4, s[10:11] offset:2048
	global_load_dwordx4 v[96:99], v1, s[6:7] offset:0
	global_load_dwordx2 v[154:155], v4, s[10:11] offset:2560
	global_load_dwordx4 v[100:103], v1, s[6:7] offset:1024
	global_load_dwordx2 v[156:157], v4, s[10:11] offset:3072
	global_load_dwordx4 v[104:107], v1, s[6:7] offset:2048
	global_load_dwordx2 v[158:159], v4, s[10:11] offset:3584
	global_load_dwordx4 v[108:111], v1, s[6:7] offset:3072
	global_load_dwordx2 v[160:161], v5, s[10:11] offset:0
	global_load_dwordx4 v[112:115], v2, s[6:7] offset:0
	global_load_dwordx2 v[162:163], v5, s[10:11] offset:512
	global_load_dwordx4 v[116:119], v2, s[6:7] offset:1024
	global_load_dwordx2 v[164:165], v5, s[10:11] offset:1024
	global_load_dwordx4 v[120:123], v2, s[6:7] offset:2048
	global_load_dwordx2 v[166:167], v5, s[10:11] offset:1536
	global_load_dwordx4 v[124:127], v2, s[6:7] offset:3072
	global_load_dwordx2 v[168:169], v5, s[10:11] offset:2048
	global_load_dwordx4 v[128:131], v3, s[6:7] offset:0
	global_load_dwordx2 v[170:171], v5, s[10:11] offset:2560
	global_load_dwordx4 v[132:135], v3, s[6:7] offset:1024
	global_load_dwordx2 v[172:173], v5, s[10:11] offset:3072
	global_load_dwordx4 v[136:139], v3, s[6:7] offset:2048
	global_load_dwordx2 v[174:175], v5, s[10:11] offset:3584
	global_load_dwordx4 v[140:143], v3, s[6:7] offset:3072
	s_add_i32 s0, s0, s3
	s_waitcnt vmcnt(30)
	v_lshlrev_b32_e32 v176, 16, v144
	v_and_b32_e32 v177, 0xffff0000, v144
	v_lshlrev_b32_e32 v178, 16, v145
	v_and_b32_e32 v179, 0xffff0000, v145
	v_pk_add_f32 v[80:81], v[80:81], v[176:177]
	v_pk_add_f32 v[82:83], v[82:83], v[178:179]
	v_mul_f32_e32 v184, v80, v80
	v_mul_f32_e32 v185, v81, v81
	v_mul_f32_e32 v186, v82, v82
	v_mul_f32_e32 v187, v83, v83
	s_waitcnt vmcnt(28)
	v_lshlrev_b32_e32 v176, 16, v146
	v_and_b32_e32 v177, 0xffff0000, v146
	v_lshlrev_b32_e32 v178, 16, v147
	v_and_b32_e32 v179, 0xffff0000, v147
	v_pk_add_f32 v[84:85], v[84:85], v[176:177]
	v_pk_add_f32 v[86:87], v[86:87], v[178:179]
	v_fmac_f32_e32 v184, v84, v84
	v_fmac_f32_e32 v185, v85, v85
	v_fmac_f32_e32 v186, v86, v86
	v_fmac_f32_e32 v187, v87, v87
	s_waitcnt vmcnt(26)
	v_lshlrev_b32_e32 v176, 16, v148
	v_and_b32_e32 v177, 0xffff0000, v148
	v_lshlrev_b32_e32 v178, 16, v149
	v_and_b32_e32 v179, 0xffff0000, v149
	v_pk_add_f32 v[88:89], v[88:89], v[176:177]
	v_pk_add_f32 v[90:91], v[90:91], v[178:179]
	v_fmac_f32_e32 v184, v88, v88
	v_fmac_f32_e32 v185, v89, v89
	v_fmac_f32_e32 v186, v90, v90
	v_fmac_f32_e32 v187, v91, v91
	s_waitcnt vmcnt(24)
	v_lshlrev_b32_e32 v176, 16, v150
	v_and_b32_e32 v177, 0xffff0000, v150
	v_lshlrev_b32_e32 v178, 16, v151
	v_and_b32_e32 v179, 0xffff0000, v151
	v_pk_add_f32 v[92:93], v[92:93], v[176:177]
	v_pk_add_f32 v[94:95], v[94:95], v[178:179]
	v_fmac_f32_e32 v184, v92, v92
	v_fmac_f32_e32 v185, v93, v93
	v_fmac_f32_e32 v186, v94, v94
	v_fmac_f32_e32 v187, v95, v95
	s_waitcnt vmcnt(22)
	v_lshlrev_b32_e32 v176, 16, v152
	v_and_b32_e32 v177, 0xffff0000, v152
	v_lshlrev_b32_e32 v178, 16, v153
	v_and_b32_e32 v179, 0xffff0000, v153
	v_pk_add_f32 v[96:97], v[96:97], v[176:177]
	v_pk_add_f32 v[98:99], v[98:99], v[178:179]
	v_fmac_f32_e32 v184, v96, v96
	v_fmac_f32_e32 v185, v97, v97
	v_fmac_f32_e32 v186, v98, v98
	v_fmac_f32_e32 v187, v99, v99
	s_waitcnt vmcnt(20)
	v_lshlrev_b32_e32 v176, 16, v154
	v_and_b32_e32 v177, 0xffff0000, v154
	v_lshlrev_b32_e32 v178, 16, v155
	v_and_b32_e32 v179, 0xffff0000, v155
	v_pk_add_f32 v[100:101], v[100:101], v[176:177]
	v_pk_add_f32 v[102:103], v[102:103], v[178:179]
	v_fmac_f32_e32 v184, v100, v100
	v_fmac_f32_e32 v185, v101, v101
	v_fmac_f32_e32 v186, v102, v102
	v_fmac_f32_e32 v187, v103, v103
	s_waitcnt vmcnt(18)
	v_lshlrev_b32_e32 v176, 16, v156
	v_and_b32_e32 v177, 0xffff0000, v156
	v_lshlrev_b32_e32 v178, 16, v157
	v_and_b32_e32 v179, 0xffff0000, v157
	v_pk_add_f32 v[104:105], v[104:105], v[176:177]
	v_pk_add_f32 v[106:107], v[106:107], v[178:179]
	v_fmac_f32_e32 v184, v104, v104
	v_fmac_f32_e32 v185, v105, v105
	v_fmac_f32_e32 v186, v106, v106
	v_fmac_f32_e32 v187, v107, v107
	s_waitcnt vmcnt(16)
	v_lshlrev_b32_e32 v176, 16, v158
	v_and_b32_e32 v177, 0xffff0000, v158
	v_lshlrev_b32_e32 v178, 16, v159
	v_and_b32_e32 v179, 0xffff0000, v159
	v_pk_add_f32 v[108:109], v[108:109], v[176:177]
	v_pk_add_f32 v[110:111], v[110:111], v[178:179]
	v_fmac_f32_e32 v184, v108, v108
	v_fmac_f32_e32 v185, v109, v109
	v_fmac_f32_e32 v186, v110, v110
	v_fmac_f32_e32 v187, v111, v111
	s_waitcnt vmcnt(14)
	v_lshlrev_b32_e32 v176, 16, v160
	v_and_b32_e32 v177, 0xffff0000, v160
	v_lshlrev_b32_e32 v178, 16, v161
	v_and_b32_e32 v179, 0xffff0000, v161
	v_pk_add_f32 v[112:113], v[112:113], v[176:177]
	v_pk_add_f32 v[114:115], v[114:115], v[178:179]
	v_fmac_f32_e32 v184, v112, v112
	v_fmac_f32_e32 v185, v113, v113
	v_fmac_f32_e32 v186, v114, v114
	v_fmac_f32_e32 v187, v115, v115
	s_waitcnt vmcnt(12)
	v_lshlrev_b32_e32 v176, 16, v162
	v_and_b32_e32 v177, 0xffff0000, v162
	v_lshlrev_b32_e32 v178, 16, v163
	v_and_b32_e32 v179, 0xffff0000, v163
	v_pk_add_f32 v[116:117], v[116:117], v[176:177]
	v_pk_add_f32 v[118:119], v[118:119], v[178:179]
	v_fmac_f32_e32 v184, v116, v116
	v_fmac_f32_e32 v185, v117, v117
	v_fmac_f32_e32 v186, v118, v118
	v_fmac_f32_e32 v187, v119, v119
	s_waitcnt vmcnt(10)
	v_lshlrev_b32_e32 v176, 16, v164
	v_and_b32_e32 v177, 0xffff0000, v164
	v_lshlrev_b32_e32 v178, 16, v165
	v_and_b32_e32 v179, 0xffff0000, v165
	v_pk_add_f32 v[120:121], v[120:121], v[176:177]
	v_pk_add_f32 v[122:123], v[122:123], v[178:179]
	v_fmac_f32_e32 v184, v120, v120
	v_fmac_f32_e32 v185, v121, v121
	v_fmac_f32_e32 v186, v122, v122
	v_fmac_f32_e32 v187, v123, v123
	s_waitcnt vmcnt(8)
	v_lshlrev_b32_e32 v176, 16, v166
	v_and_b32_e32 v177, 0xffff0000, v166
	v_lshlrev_b32_e32 v178, 16, v167
	v_and_b32_e32 v179, 0xffff0000, v167
	v_pk_add_f32 v[124:125], v[124:125], v[176:177]
	v_pk_add_f32 v[126:127], v[126:127], v[178:179]
	v_fmac_f32_e32 v184, v124, v124
	v_fmac_f32_e32 v185, v125, v125
	v_fmac_f32_e32 v186, v126, v126
	v_fmac_f32_e32 v187, v127, v127
	s_waitcnt vmcnt(6)
	v_lshlrev_b32_e32 v176, 16, v168
	v_and_b32_e32 v177, 0xffff0000, v168
	v_lshlrev_b32_e32 v178, 16, v169
	v_and_b32_e32 v179, 0xffff0000, v169
	v_pk_add_f32 v[128:129], v[128:129], v[176:177]
	v_pk_add_f32 v[130:131], v[130:131], v[178:179]
	v_fmac_f32_e32 v184, v128, v128
	v_fmac_f32_e32 v185, v129, v129
	v_fmac_f32_e32 v186, v130, v130
	v_fmac_f32_e32 v187, v131, v131
	s_waitcnt vmcnt(4)
	v_lshlrev_b32_e32 v176, 16, v170
	v_and_b32_e32 v177, 0xffff0000, v170
	v_lshlrev_b32_e32 v178, 16, v171
	v_and_b32_e32 v179, 0xffff0000, v171
	v_pk_add_f32 v[132:133], v[132:133], v[176:177]
	v_pk_add_f32 v[134:135], v[134:135], v[178:179]
	v_fmac_f32_e32 v184, v132, v132
	v_fmac_f32_e32 v185, v133, v133
	v_fmac_f32_e32 v186, v134, v134
	v_fmac_f32_e32 v187, v135, v135
	s_waitcnt vmcnt(2)
	v_lshlrev_b32_e32 v176, 16, v172
	v_and_b32_e32 v177, 0xffff0000, v172
	v_lshlrev_b32_e32 v178, 16, v173
	v_and_b32_e32 v179, 0xffff0000, v173
	v_pk_add_f32 v[136:137], v[136:137], v[176:177]
	v_pk_add_f32 v[138:139], v[138:139], v[178:179]
	v_fmac_f32_e32 v184, v136, v136
	v_fmac_f32_e32 v185, v137, v137
	v_fmac_f32_e32 v186, v138, v138
	v_fmac_f32_e32 v187, v139, v139
	s_waitcnt vmcnt(0)
	v_lshlrev_b32_e32 v176, 16, v174
	v_and_b32_e32 v177, 0xffff0000, v174
	v_lshlrev_b32_e32 v178, 16, v175
	v_and_b32_e32 v179, 0xffff0000, v175
	v_pk_add_f32 v[140:141], v[140:141], v[176:177]
	v_pk_add_f32 v[142:143], v[142:143], v[178:179]
	v_fmac_f32_e32 v184, v140, v140
	v_fmac_f32_e32 v185, v141, v141
	v_fmac_f32_e32 v186, v142, v142
	v_fmac_f32_e32 v187, v143, v143
	v_add_f32_e32 v184, v184, v185
	v_add_f32_e32 v186, v186, v187
	v_add_f32_e32 v184, v184, v186
	ds_bpermute_b32 v185, v8, v184
	s_waitcnt lgkmcnt(0)
	v_add_f32_e32 v184, v184, v185
	ds_bpermute_b32 v185, v9, v184
	s_waitcnt lgkmcnt(0)
	v_add_f32_e32 v184, v184, v185
	ds_bpermute_b32 v185, v10, v184
	s_waitcnt lgkmcnt(0)
	v_add_f32_e32 v184, v184, v185
	ds_bpermute_b32 v185, v11, v184
	s_waitcnt lgkmcnt(0)
	v_add_f32_e32 v184, v184, v185
	ds_bpermute_b32 v185, v12, v184
	s_waitcnt lgkmcnt(0)
	v_add_f32_e32 v184, v184, v185
	ds_bpermute_b32 v185, v13, v184
	s_waitcnt lgkmcnt(0)
	v_add_f32_e32 v184, v184, v185
	v_fmamk_f32 v184, v184, 0x39800000, v14
	v_rsq_f32_e32 v184, v184
	s_nop 0
	v_pk_mul_f32 v[80:81], v[80:81], v[184:185] op_sel_hi:[1,0]
	v_pk_mul_f32 v[82:83], v[82:83], v[184:185] op_sel_hi:[1,0]
	v_pk_mul_f32 v[80:81], v[80:81], v[16:17]
	v_pk_mul_f32 v[82:83], v[82:83], v[18:19]
	global_store_dwordx4 v0, v[80:83], s[8:9] offset:0
	v_pk_mul_f32 v[84:85], v[84:85], v[184:185] op_sel_hi:[1,0]
	v_pk_mul_f32 v[86:87], v[86:87], v[184:185] op_sel_hi:[1,0]
	v_pk_mul_f32 v[84:85], v[84:85], v[20:21]
	v_pk_mul_f32 v[86:87], v[86:87], v[22:23]
	global_store_dwordx4 v0, v[84:87], s[8:9] offset:1024
	v_pk_mul_f32 v[88:89], v[88:89], v[184:185] op_sel_hi:[1,0]
	v_pk_mul_f32 v[90:91], v[90:91], v[184:185] op_sel_hi:[1,0]
	v_pk_mul_f32 v[88:89], v[88:89], v[24:25]
	v_pk_mul_f32 v[90:91], v[90:91], v[26:27]
	global_store_dwordx4 v0, v[88:91], s[8:9] offset:2048
	v_pk_mul_f32 v[92:93], v[92:93], v[184:185] op_sel_hi:[1,0]
	v_pk_mul_f32 v[94:95], v[94:95], v[184:185] op_sel_hi:[1,0]
	v_pk_mul_f32 v[92:93], v[92:93], v[28:29]
	v_pk_mul_f32 v[94:95], v[94:95], v[30:31]
	global_store_dwordx4 v0, v[92:95], s[8:9] offset:3072
	v_pk_mul_f32 v[96:97], v[96:97], v[184:185] op_sel_hi:[1,0]
	v_pk_mul_f32 v[98:99], v[98:99], v[184:185] op_sel_hi:[1,0]
	v_pk_mul_f32 v[96:97], v[96:97], v[32:33]
	v_pk_mul_f32 v[98:99], v[98:99], v[34:35]
	global_store_dwordx4 v1, v[96:99], s[8:9] offset:0
	v_pk_mul_f32 v[100:101], v[100:101], v[184:185] op_sel_hi:[1,0]
	v_pk_mul_f32 v[102:103], v[102:103], v[184:185] op_sel_hi:[1,0]
	v_pk_mul_f32 v[100:101], v[100:101], v[36:37]
	v_pk_mul_f32 v[102:103], v[102:103], v[38:39]
	global_store_dwordx4 v1, v[100:103], s[8:9] offset:1024
	v_pk_mul_f32 v[104:105], v[104:105], v[184:185] op_sel_hi:[1,0]
	v_pk_mul_f32 v[106:107], v[106:107], v[184:185] op_sel_hi:[1,0]
	v_pk_mul_f32 v[104:105], v[104:105], v[40:41]
	v_pk_mul_f32 v[106:107], v[106:107], v[42:43]
	global_store_dwordx4 v1, v[104:107], s[8:9] offset:2048
	v_pk_mul_f32 v[108:109], v[108:109], v[184:185] op_sel_hi:[1,0]
	v_pk_mul_f32 v[110:111], v[110:111], v[184:185] op_sel_hi:[1,0]
	v_pk_mul_f32 v[108:109], v[108:109], v[44:45]
	v_pk_mul_f32 v[110:111], v[110:111], v[46:47]
	global_store_dwordx4 v1, v[108:111], s[8:9] offset:3072
	v_pk_mul_f32 v[112:113], v[112:113], v[184:185] op_sel_hi:[1,0]
	v_pk_mul_f32 v[114:115], v[114:115], v[184:185] op_sel_hi:[1,0]
	v_pk_mul_f32 v[112:113], v[112:113], v[48:49]
	v_pk_mul_f32 v[114:115], v[114:115], v[50:51]
	global_store_dwordx4 v2, v[112:115], s[8:9] offset:0
	v_pk_mul_f32 v[116:117], v[116:117], v[184:185] op_sel_hi:[1,0]
	v_pk_mul_f32 v[118:119], v[118:119], v[184:185] op_sel_hi:[1,0]
	v_pk_mul_f32 v[116:117], v[116:117], v[52:53]
	v_pk_mul_f32 v[118:119], v[118:119], v[54:55]
	global_store_dwordx4 v2, v[116:119], s[8:9] offset:1024
	v_pk_mul_f32 v[120:121], v[120:121], v[184:185] op_sel_hi:[1,0]
	v_pk_mul_f32 v[122:123], v[122:123], v[184:185] op_sel_hi:[1,0]
	v_pk_mul_f32 v[120:121], v[120:121], v[56:57]
	v_pk_mul_f32 v[122:123], v[122:123], v[58:59]
	global_store_dwordx4 v2, v[120:123], s[8:9] offset:2048
	v_pk_mul_f32 v[124:125], v[124:125], v[184:185] op_sel_hi:[1,0]
	v_pk_mul_f32 v[126:127], v[126:127], v[184:185] op_sel_hi:[1,0]
	v_pk_mul_f32 v[124:125], v[124:125], v[60:61]
	v_pk_mul_f32 v[126:127], v[126:127], v[62:63]
	global_store_dwordx4 v2, v[124:127], s[8:9] offset:3072
	v_pk_mul_f32 v[128:129], v[128:129], v[184:185] op_sel_hi:[1,0]
	v_pk_mul_f32 v[130:131], v[130:131], v[184:185] op_sel_hi:[1,0]
	v_pk_mul_f32 v[128:129], v[128:129], v[64:65]
	v_pk_mul_f32 v[130:131], v[130:131], v[66:67]
	global_store_dwordx4 v3, v[128:131], s[8:9] offset:0
	v_pk_mul_f32 v[132:133], v[132:133], v[184:185] op_sel_hi:[1,0]
	v_pk_mul_f32 v[134:135], v[134:135], v[184:185] op_sel_hi:[1,0]
	v_pk_mul_f32 v[132:133], v[132:133], v[68:69]
	v_pk_mul_f32 v[134:135], v[134:135], v[70:71]
	global_store_dwordx4 v3, v[132:135], s[8:9] offset:1024
	v_pk_mul_f32 v[136:137], v[136:137], v[184:185] op_sel_hi:[1,0]
	v_pk_mul_f32 v[138:139], v[138:139], v[184:185] op_sel_hi:[1,0]
	v_pk_mul_f32 v[136:137], v[136:137], v[72:73]
	v_pk_mul_f32 v[138:139], v[138:139], v[74:75]
	global_store_dwordx4 v3, v[136:139], s[8:9] offset:2048
	v_pk_mul_f32 v[140:141], v[140:141], v[184:185] op_sel_hi:[1,0]
	v_pk_mul_f32 v[142:143], v[142:143], v[184:185] op_sel_hi:[1,0]
	v_pk_mul_f32 v[140:141], v[140:141], v[76:77]
	v_pk_mul_f32 v[142:143], v[142:143], v[78:79]
	global_store_dwordx4 v3, v[140:143], s[8:9] offset:3072
	s_cmpk_lt_i32 s0, 0x2000
	s_cbranch_scc1 .Lp5_row
